# GEMM accumulator zeroing between tiles done with 64-bit moves
# speedup vs baseline: 1.0084x; 1.0084x over previous
.LBB0_504:
	s_ashr_i32 s13, s12, 31
	s_lshl_b64 s[14:15], s[12:13], 19
	s_add_u32 s14, s24, s14
	s_addc_u32 s15, s25, s15
	s_ashr_i32 s11, s10, 31
	s_lshl_b64 s[16:17], s[10:11], 19
	s_add_u32 s16, s28, s16
	v_mov_b64_e32 v[0:1], 0
	v_mov_b64_e32 v[2:3], 0
	v_mov_b64_e32 v[4:5], 0
	v_mov_b64_e32 v[6:7], 0
	v_mov_b64_e32 v[8:9], 0
	v_mov_b64_e32 v[10:11], 0
	v_mov_b64_e32 v[12:13], 0
	v_mov_b64_e32 v[14:15], 0
	v_mov_b64_e32 v[16:17], 0
	v_mov_b64_e32 v[18:19], 0
	v_mov_b64_e32 v[20:21], 0
	v_mov_b64_e32 v[22:23], 0
	v_mov_b64_e32 v[24:25], 0
	v_mov_b64_e32 v[26:27], 0
	v_mov_b64_e32 v[28:29], 0
	v_mov_b64_e32 v[30:31], 0
	v_mov_b64_e32 v[32:33], 0
	v_mov_b64_e32 v[34:35], 0
	v_mov_b64_e32 v[36:37], 0
	v_mov_b64_e32 v[38:39], 0
	v_mov_b64_e32 v[40:41], 0
	v_mov_b64_e32 v[42:43], 0
	v_mov_b64_e32 v[44:45], 0
	v_mov_b64_e32 v[46:47], 0
	v_mov_b64_e32 v[48:49], 0
	v_mov_b64_e32 v[50:51], 0
	v_mov_b64_e32 v[52:53], 0
	v_mov_b64_e32 v[54:55], 0
	v_mov_b64_e32 v[56:57], 0
	v_mov_b64_e32 v[58:59], 0
	v_mov_b64_e32 v[60:61], 0
	v_mov_b64_e32 v[62:63], 0
	v_mov_b64_e32 v[64:65], 0
	v_mov_b64_e32 v[66:67], 0
	v_mov_b64_e32 v[68:69], 0
	v_mov_b64_e32 v[70:71], 0
	v_mov_b64_e32 v[72:73], 0
	v_mov_b64_e32 v[74:75], 0
	v_mov_b64_e32 v[76:77], 0
	v_mov_b64_e32 v[78:79], 0
	v_mov_b64_e32 v[80:81], 0
	v_mov_b64_e32 v[82:83], 0
	v_mov_b64_e32 v[84:85], 0
	v_mov_b64_e32 v[86:87], 0
	v_mov_b64_e32 v[88:89], 0
	v_mov_b64_e32 v[90:91], 0
	v_mov_b64_e32 v[92:93], 0
	v_mov_b64_e32 v[94:95], 0
	v_mov_b64_e32 v[96:97], 0
	v_mov_b64_e32 v[98:99], 0
	v_mov_b64_e32 v[100:101], 0
	v_mov_b64_e32 v[102:103], 0
	v_mov_b64_e32 v[104:105], 0
	v_mov_b64_e32 v[106:107], 0
	v_mov_b64_e32 v[108:109], 0
	v_mov_b64_e32 v[110:111], 0
	v_mov_b64_e32 v[112:113], 0
	v_mov_b64_e32 v[114:115], 0
	v_mov_b64_e32 v[116:117], 0
	v_mov_b64_e32 v[118:119], 0
	v_mov_b64_e32 v[120:121], 0
	v_mov_b64_e32 v[122:123], 0
	v_mov_b64_e32 v[124:125], 0
	v_mov_b64_e32 v[126:127], 0
	s_addc_u32 s17, s40, s17
	s_andn2_b64 vcc, exec, s[8:9]
	s_cbranch_vccnz .LBB0_507
	s_and_b64 s[18:19], s[36:37], exec
	s_cselect_b32 s11, s15, s3
	s_cselect_b32 s13, s14, s2
	s_cselect_b32 s26, s17, s1
	s_cselect_b32 s27, s16, s0
	s_add_u32 s34, s0, 0x100
	s_addc_u32 s35, s1, 0
	s_add_u32 s0, s2, 0x40080
	v_mov_b64_e32 v[0:1], 0
	v_mov_b64_e32 v[2:3], 0
	v_mov_b64_e32 v[4:5], 0
	v_mov_b64_e32 v[6:7], 0
	v_mov_b64_e32 v[8:9], 0
	v_mov_b64_e32 v[10:11], 0
	v_mov_b64_e32 v[12:13], 0
	v_mov_b64_e32 v[14:15], 0
	v_mov_b64_e32 v[16:17], 0
	v_mov_b64_e32 v[18:19], 0
	v_mov_b64_e32 v[20:21], 0
	v_mov_b64_e32 v[22:23], 0
	v_mov_b64_e32 v[24:25], 0
	v_mov_b64_e32 v[26:27], 0
	v_mov_b64_e32 v[28:29], 0
	v_mov_b64_e32 v[30:31], 0
	v_mov_b64_e32 v[32:33], 0
	v_mov_b64_e32 v[34:35], 0
	v_mov_b64_e32 v[36:37], 0
	v_mov_b64_e32 v[38:39], 0
	v_mov_b64_e32 v[40:41], 0
	v_mov_b64_e32 v[42:43], 0
	v_mov_b64_e32 v[44:45], 0
	v_mov_b64_e32 v[46:47], 0
	v_mov_b64_e32 v[48:49], 0
	v_mov_b64_e32 v[50:51], 0
	v_mov_b64_e32 v[52:53], 0
	v_mov_b64_e32 v[54:55], 0
	v_mov_b64_e32 v[56:57], 0
	v_mov_b64_e32 v[58:59], 0
	v_mov_b64_e32 v[60:61], 0
	v_mov_b64_e32 v[62:63], 0
	v_mov_b64_e32 v[64:65], 0
	v_mov_b64_e32 v[66:67], 0
	v_mov_b64_e32 v[68:69], 0
	v_mov_b64_e32 v[70:71], 0
	v_mov_b64_e32 v[72:73], 0
	v_mov_b64_e32 v[74:75], 0
	v_mov_b64_e32 v[76:77], 0
	v_mov_b64_e32 v[78:79], 0
	v_mov_b64_e32 v[80:81], 0
	v_mov_b64_e32 v[82:83], 0
	v_mov_b64_e32 v[84:85], 0
	v_mov_b64_e32 v[86:87], 0
	v_mov_b64_e32 v[88:89], 0
	v_mov_b64_e32 v[90:91], 0
	v_mov_b64_e32 v[92:93], 0
	v_mov_b64_e32 v[94:95], 0
	v_mov_b64_e32 v[96:97], 0
	v_mov_b64_e32 v[98:99], 0
	v_mov_b64_e32 v[100:101], 0
	v_mov_b64_e32 v[102:103], 0
	v_mov_b64_e32 v[104:105], 0
	v_mov_b64_e32 v[106:107], 0
	v_mov_b64_e32 v[108:109], 0
	v_mov_b64_e32 v[110:111], 0
	v_mov_b64_e32 v[112:113], 0
	v_mov_b64_e32 v[114:115], 0
	v_mov_b64_e32 v[116:117], 0
	v_mov_b64_e32 v[118:119], 0
	v_mov_b64_e32 v[120:121], 0
	v_mov_b64_e32 v[122:123], 0
	v_mov_b64_e32 v[124:125], 0
	v_mov_b64_e32 v[126:127], 0
	s_addc_u32 s1, s3, 0
	s_mov_b32 s2, 0

.LBB0_633:
	s_ashr_i32 s19, s18, 31
	s_lshl_b64 s[24:25], s[18:19], 17
	s_add_u32 s40, s47, s24
	v_mov_b64_e32 v[0:1], 0
	v_mov_b64_e32 v[2:3], 0
	v_mov_b64_e32 v[4:5], 0
	v_mov_b64_e32 v[6:7], 0
	v_mov_b64_e32 v[8:9], 0
	v_mov_b64_e32 v[10:11], 0
	v_mov_b64_e32 v[12:13], 0
	v_mov_b64_e32 v[14:15], 0
	v_mov_b64_e32 v[16:17], 0
	v_mov_b64_e32 v[18:19], 0
	v_mov_b64_e32 v[20:21], 0
	v_mov_b64_e32 v[22:23], 0
	v_mov_b64_e32 v[24:25], 0
	v_mov_b64_e32 v[26:27], 0
	v_mov_b64_e32 v[28:29], 0
	v_mov_b64_e32 v[30:31], 0
	v_mov_b64_e32 v[32:33], 0
	v_mov_b64_e32 v[34:35], 0
	v_mov_b64_e32 v[36:37], 0
	v_mov_b64_e32 v[38:39], 0
	v_mov_b64_e32 v[40:41], 0
	v_mov_b64_e32 v[42:43], 0
	v_mov_b64_e32 v[44:45], 0
	v_mov_b64_e32 v[46:47], 0
	v_mov_b64_e32 v[48:49], 0
	v_mov_b64_e32 v[50:51], 0
	v_mov_b64_e32 v[52:53], 0
	v_mov_b64_e32 v[54:55], 0
	v_mov_b64_e32 v[56:57], 0
	v_mov_b64_e32 v[58:59], 0
	v_mov_b64_e32 v[60:61], 0
	v_mov_b64_e32 v[62:63], 0
	v_mov_b64_e32 v[68:69], 0
	v_mov_b64_e32 v[70:71], 0
	v_mov_b64_e32 v[72:73], 0
	v_mov_b64_e32 v[74:75], 0
	v_mov_b64_e32 v[76:77], 0
	v_mov_b64_e32 v[78:79], 0
	v_mov_b64_e32 v[80:81], 0
	v_mov_b64_e32 v[82:83], 0
	v_mov_b64_e32 v[84:85], 0
	v_mov_b64_e32 v[86:87], 0
	v_mov_b64_e32 v[88:89], 0
	v_mov_b64_e32 v[90:91], 0
	v_mov_b64_e32 v[92:93], 0
	v_mov_b64_e32 v[94:95], 0
	v_mov_b64_e32 v[96:97], 0
	v_mov_b64_e32 v[98:99], 0
	v_mov_b64_e32 v[100:101], 0
	v_mov_b64_e32 v[102:103], 0
	v_mov_b64_e32 v[104:105], 0
	v_mov_b64_e32 v[106:107], 0
	v_mov_b64_e32 v[108:109], 0
	v_mov_b64_e32 v[110:111], 0
	v_mov_b64_e32 v[112:113], 0
	v_mov_b64_e32 v[114:115], 0
	v_mov_b64_e32 v[116:117], 0
	v_mov_b64_e32 v[118:119], 0
	v_mov_b64_e32 v[120:121], 0
	v_mov_b64_e32 v[122:123], 0
	v_mov_b64_e32 v[124:125], 0
	v_mov_b64_e32 v[126:127], 0
	v_mov_b64_e32 v[128:129], 0
	v_mov_b64_e32 v[130:131], 0
	s_addc_u32 s41, s48, s25
	s_andn2_b64 vcc, exec, s[16:17]
	s_cbranch_vccnz .LBB0_636
	s_and_b64 s[0:1], s[0:1], exec
	s_cselect_b32 s3, s41, s43
	s_cselect_b32 s19, s40, s42
	s_add_u32 s21, s42, 0x100
	v_mov_b64_e32 v[0:1], 0
	v_mov_b64_e32 v[2:3], 0
	v_mov_b64_e32 v[4:5], 0
	v_mov_b64_e32 v[6:7], 0
	v_mov_b64_e32 v[8:9], 0
	v_mov_b64_e32 v[10:11], 0
	v_mov_b64_e32 v[12:13], 0
	v_mov_b64_e32 v[14:15], 0
	v_mov_b64_e32 v[16:17], 0
	v_mov_b64_e32 v[18:19], 0
	v_mov_b64_e32 v[20:21], 0
	v_mov_b64_e32 v[22:23], 0
	v_mov_b64_e32 v[24:25], 0
	v_mov_b64_e32 v[26:27], 0
	v_mov_b64_e32 v[28:29], 0
	v_mov_b64_e32 v[30:31], 0
	v_mov_b64_e32 v[32:33], 0
	v_mov_b64_e32 v[34:35], 0
	v_mov_b64_e32 v[36:37], 0
	v_mov_b64_e32 v[38:39], 0
	v_mov_b64_e32 v[40:41], 0
	v_mov_b64_e32 v[42:43], 0
	v_mov_b64_e32 v[44:45], 0
	v_mov_b64_e32 v[46:47], 0
	v_mov_b64_e32 v[48:49], 0
	v_mov_b64_e32 v[50:51], 0
	v_mov_b64_e32 v[52:53], 0
	v_mov_b64_e32 v[54:55], 0
	v_mov_b64_e32 v[56:57], 0
	v_mov_b64_e32 v[58:59], 0
	v_mov_b64_e32 v[60:61], 0
	v_mov_b64_e32 v[62:63], 0
	v_mov_b64_e32 v[68:69], 0
	v_mov_b64_e32 v[70:71], 0
	v_mov_b64_e32 v[72:73], 0
	v_mov_b64_e32 v[74:75], 0
	v_mov_b64_e32 v[76:77], 0
	v_mov_b64_e32 v[78:79], 0
	v_mov_b64_e32 v[80:81], 0
	v_mov_b64_e32 v[82:83], 0
	v_mov_b64_e32 v[84:85], 0
	v_mov_b64_e32 v[86:87], 0
	v_mov_b64_e32 v[88:89], 0
	v_mov_b64_e32 v[90:91], 0
	v_mov_b64_e32 v[92:93], 0
	v_mov_b64_e32 v[94:95], 0
	v_mov_b64_e32 v[96:97], 0
	v_mov_b64_e32 v[98:99], 0
	v_mov_b64_e32 v[100:101], 0
	v_mov_b64_e32 v[102:103], 0
	v_mov_b64_e32 v[104:105], 0
	v_mov_b64_e32 v[106:107], 0
	v_mov_b64_e32 v[108:109], 0
	v_mov_b64_e32 v[110:111], 0
	v_mov_b64_e32 v[112:113], 0
	v_mov_b64_e32 v[114:115], 0
	v_mov_b64_e32 v[116:117], 0
	v_mov_b64_e32 v[118:119], 0
	v_mov_b64_e32 v[120:121], 0
	v_mov_b64_e32 v[122:123], 0
	v_mov_b64_e32 v[124:125], 0
	v_mov_b64_e32 v[126:127], 0
	v_mov_b64_e32 v[128:129], 0
	v_mov_b64_e32 v[130:131], 0
	s_addc_u32 s24, s43, 0
	s_mov_b32 s25, 0

.LBB0_668:
	s_ashr_i32 s15, s14, 31
	s_lshl_b64 s[18:19], s[14:15], 16
	s_add_u32 s18, s26, s18
	v_mov_b64_e32 v[0:1], 0
	v_mov_b64_e32 v[2:3], 0
	v_mov_b64_e32 v[4:5], 0
	v_mov_b64_e32 v[6:7], 0
	v_mov_b64_e32 v[8:9], 0
	v_mov_b64_e32 v[10:11], 0
	v_mov_b64_e32 v[12:13], 0
	v_mov_b64_e32 v[14:15], 0
	v_mov_b64_e32 v[16:17], 0
	v_mov_b64_e32 v[18:19], 0
	v_mov_b64_e32 v[20:21], 0
	v_mov_b64_e32 v[22:23], 0
	v_mov_b64_e32 v[24:25], 0
	v_mov_b64_e32 v[26:27], 0
	v_mov_b64_e32 v[28:29], 0
	v_mov_b64_e32 v[30:31], 0
	v_mov_b64_e32 v[32:33], 0
	v_mov_b64_e32 v[34:35], 0
	v_mov_b64_e32 v[36:37], 0
	v_mov_b64_e32 v[38:39], 0
	v_mov_b64_e32 v[40:41], 0
	v_mov_b64_e32 v[42:43], 0
	v_mov_b64_e32 v[44:45], 0
	v_mov_b64_e32 v[46:47], 0
	v_mov_b64_e32 v[48:49], 0
	v_mov_b64_e32 v[50:51], 0
	v_mov_b64_e32 v[52:53], 0
	v_mov_b64_e32 v[54:55], 0
	v_mov_b64_e32 v[56:57], 0
	v_mov_b64_e32 v[58:59], 0
	v_mov_b64_e32 v[60:61], 0
	v_mov_b64_e32 v[62:63], 0
	v_mov_b64_e32 v[64:65], 0
	v_mov_b64_e32 v[66:67], 0
	v_mov_b64_e32 v[68:69], 0
	v_mov_b64_e32 v[70:71], 0
	v_mov_b64_e32 v[72:73], 0
	v_mov_b64_e32 v[74:75], 0
	v_mov_b64_e32 v[76:77], 0
	v_mov_b64_e32 v[78:79], 0
	v_mov_b64_e32 v[80:81], 0
	v_mov_b64_e32 v[82:83], 0
	v_mov_b64_e32 v[84:85], 0
	v_mov_b64_e32 v[86:87], 0
	v_mov_b64_e32 v[88:89], 0
	v_mov_b64_e32 v[90:91], 0
	v_mov_b64_e32 v[92:93], 0
	v_mov_b64_e32 v[94:95], 0
	v_mov_b64_e32 v[96:97], 0
	v_mov_b64_e32 v[98:99], 0
	v_mov_b64_e32 v[100:101], 0
	v_mov_b64_e32 v[102:103], 0
	v_mov_b64_e32 v[104:105], 0
	v_mov_b64_e32 v[106:107], 0
	v_mov_b64_e32 v[108:109], 0
	v_mov_b64_e32 v[110:111], 0
	v_mov_b64_e32 v[112:113], 0
	v_mov_b64_e32 v[114:115], 0
	v_mov_b64_e32 v[116:117], 0
	v_mov_b64_e32 v[118:119], 0
	v_mov_b64_e32 v[120:121], 0
	v_mov_b64_e32 v[122:123], 0
	v_mov_b64_e32 v[124:125], 0
	v_mov_b64_e32 v[126:127], 0
	s_addc_u32 s19, s27, s19
	s_andn2_b64 vcc, exec, s[10:11]
	s_cbranch_vccnz .LBB0_671
	s_and_b64 s[2:3], s[2:3], exec
	s_cselect_b32 s15, s19, s39
	s_cselect_b32 s48, s18, s38
	s_add_u32 s49, s38, 0x100
	v_mov_b64_e32 v[0:1], 0
	v_mov_b64_e32 v[2:3], 0
	v_mov_b64_e32 v[4:5], 0
	v_mov_b64_e32 v[6:7], 0
	v_mov_b64_e32 v[8:9], 0
	v_mov_b64_e32 v[10:11], 0
	v_mov_b64_e32 v[12:13], 0
	v_mov_b64_e32 v[14:15], 0
	v_mov_b64_e32 v[16:17], 0
	v_mov_b64_e32 v[18:19], 0
	v_mov_b64_e32 v[20:21], 0
	v_mov_b64_e32 v[22:23], 0
	v_mov_b64_e32 v[24:25], 0
	v_mov_b64_e32 v[26:27], 0
	v_mov_b64_e32 v[28:29], 0
	v_mov_b64_e32 v[30:31], 0
	v_mov_b64_e32 v[32:33], 0
	v_mov_b64_e32 v[34:35], 0
	v_mov_b64_e32 v[36:37], 0
	v_mov_b64_e32 v[38:39], 0
	v_mov_b64_e32 v[40:41], 0
	v_mov_b64_e32 v[42:43], 0
	v_mov_b64_e32 v[44:45], 0
	v_mov_b64_e32 v[46:47], 0
	v_mov_b64_e32 v[48:49], 0
	v_mov_b64_e32 v[50:51], 0
	v_mov_b64_e32 v[52:53], 0
	v_mov_b64_e32 v[54:55], 0
	v_mov_b64_e32 v[56:57], 0
	v_mov_b64_e32 v[58:59], 0
	v_mov_b64_e32 v[60:61], 0
	v_mov_b64_e32 v[62:63], 0
	v_mov_b64_e32 v[64:65], 0
	v_mov_b64_e32 v[66:67], 0
	v_mov_b64_e32 v[68:69], 0
	v_mov_b64_e32 v[70:71], 0
	v_mov_b64_e32 v[72:73], 0
	v_mov_b64_e32 v[74:75], 0
	v_mov_b64_e32 v[76:77], 0
	v_mov_b64_e32 v[78:79], 0
	v_mov_b64_e32 v[80:81], 0
	v_mov_b64_e32 v[82:83], 0
	v_mov_b64_e32 v[84:85], 0
	v_mov_b64_e32 v[86:87], 0
	v_mov_b64_e32 v[88:89], 0
	v_mov_b64_e32 v[90:91], 0
	v_mov_b64_e32 v[92:93], 0
	v_mov_b64_e32 v[94:95], 0
	v_mov_b64_e32 v[96:97], 0
	v_mov_b64_e32 v[98:99], 0
	v_mov_b64_e32 v[100:101], 0
	v_mov_b64_e32 v[102:103], 0
	v_mov_b64_e32 v[104:105], 0
	v_mov_b64_e32 v[106:107], 0
	v_mov_b64_e32 v[108:109], 0
	v_mov_b64_e32 v[110:111], 0
	v_mov_b64_e32 v[112:113], 0
	v_mov_b64_e32 v[114:115], 0
	v_mov_b64_e32 v[116:117], 0
	v_mov_b64_e32 v[118:119], 0
	v_mov_b64_e32 v[120:121], 0
	v_mov_b64_e32 v[122:123], 0
	v_mov_b64_e32 v[124:125], 0
	v_mov_b64_e32 v[126:127], 0
	s_addc_u32 s50, s39, 0
	s_mov_b32 s38, 0

.LBB0_1170:
	s_ashr_i32 s17, s16, 31
	s_lshl_b64 s[18:19], s[16:17], 19
	s_add_u32 s18, s20, s18
	s_addc_u32 s19, s21, s19
	s_ashr_i32 s15, s14, 31
	s_lshl_b64 s[24:25], s[14:15], 19
	s_add_u32 s36, s28, s24
	v_mov_b64_e32 v[0:1], 0
	v_mov_b64_e32 v[2:3], 0
	v_mov_b64_e32 v[4:5], 0
	v_mov_b64_e32 v[6:7], 0
	v_mov_b64_e32 v[8:9], 0
	v_mov_b64_e32 v[10:11], 0
	v_mov_b64_e32 v[12:13], 0
	v_mov_b64_e32 v[14:15], 0
	v_mov_b64_e32 v[16:17], 0
	v_mov_b64_e32 v[18:19], 0
	v_mov_b64_e32 v[20:21], 0
	v_mov_b64_e32 v[22:23], 0
	v_mov_b64_e32 v[24:25], 0
	v_mov_b64_e32 v[26:27], 0
	v_mov_b64_e32 v[28:29], 0
	v_mov_b64_e32 v[30:31], 0
	v_mov_b64_e32 v[32:33], 0
	v_mov_b64_e32 v[34:35], 0
	v_mov_b64_e32 v[36:37], 0
	v_mov_b64_e32 v[38:39], 0
	v_mov_b64_e32 v[40:41], 0
	v_mov_b64_e32 v[42:43], 0
	v_mov_b64_e32 v[44:45], 0
	v_mov_b64_e32 v[46:47], 0
	v_mov_b64_e32 v[48:49], 0
	v_mov_b64_e32 v[50:51], 0
	v_mov_b64_e32 v[52:53], 0
	v_mov_b64_e32 v[54:55], 0
	v_mov_b64_e32 v[56:57], 0
	v_mov_b64_e32 v[58:59], 0
	v_mov_b64_e32 v[60:61], 0
	v_mov_b64_e32 v[62:63], 0
	v_mov_b64_e32 v[64:65], 0
	v_mov_b64_e32 v[66:67], 0
	v_mov_b64_e32 v[68:69], 0
	v_mov_b64_e32 v[70:71], 0
	v_mov_b64_e32 v[72:73], 0
	v_mov_b64_e32 v[74:75], 0
	v_mov_b64_e32 v[76:77], 0
	v_mov_b64_e32 v[78:79], 0
	v_mov_b64_e32 v[80:81], 0
	v_mov_b64_e32 v[82:83], 0
	v_mov_b64_e32 v[84:85], 0
	v_mov_b64_e32 v[86:87], 0
	v_mov_b64_e32 v[88:89], 0
	v_mov_b64_e32 v[90:91], 0
	v_mov_b64_e32 v[92:93], 0
	v_mov_b64_e32 v[94:95], 0
	v_mov_b64_e32 v[96:97], 0
	v_mov_b64_e32 v[98:99], 0
	v_mov_b64_e32 v[100:101], 0
	v_mov_b64_e32 v[102:103], 0
	v_mov_b64_e32 v[104:105], 0
	v_mov_b64_e32 v[106:107], 0
	v_mov_b64_e32 v[108:109], 0
	v_mov_b64_e32 v[110:111], 0
	v_mov_b64_e32 v[112:113], 0
	v_mov_b64_e32 v[114:115], 0
	v_mov_b64_e32 v[116:117], 0
	v_mov_b64_e32 v[118:119], 0
	v_mov_b64_e32 v[120:121], 0
	v_mov_b64_e32 v[122:123], 0
	v_mov_b64_e32 v[124:125], 0
	v_mov_b64_e32 v[126:127], 0
	s_addc_u32 s37, s29, s25
	s_andn2_b64 vcc, exec, s[12:13]
	s_cbranch_vccnz .LBB0_1173
	s_and_b64 s[24:25], s[2:3], exec
	s_cselect_b32 s15, s19, s45
	s_cselect_b32 s17, s18, s44
	s_cselect_b32 s24, s37, s43
	s_cselect_b32 s25, s36, s42
	s_add_u32 s26, s42, 0x100
	s_addc_u32 s27, s43, 0
	s_add_u32 s42, s44, 0x40080
	v_mov_b64_e32 v[0:1], 0
	v_mov_b64_e32 v[2:3], 0
	v_mov_b64_e32 v[4:5], 0
	v_mov_b64_e32 v[6:7], 0
	v_mov_b64_e32 v[8:9], 0
	v_mov_b64_e32 v[10:11], 0
	v_mov_b64_e32 v[12:13], 0
	v_mov_b64_e32 v[14:15], 0
	v_mov_b64_e32 v[16:17], 0
	v_mov_b64_e32 v[18:19], 0
	v_mov_b64_e32 v[20:21], 0
	v_mov_b64_e32 v[22:23], 0
	v_mov_b64_e32 v[24:25], 0
	v_mov_b64_e32 v[26:27], 0
	v_mov_b64_e32 v[28:29], 0
	v_mov_b64_e32 v[30:31], 0
	v_mov_b64_e32 v[32:33], 0
	v_mov_b64_e32 v[34:35], 0
	v_mov_b64_e32 v[36:37], 0
	v_mov_b64_e32 v[38:39], 0
	v_mov_b64_e32 v[40:41], 0
	v_mov_b64_e32 v[42:43], 0
	v_mov_b64_e32 v[44:45], 0
	v_mov_b64_e32 v[46:47], 0
	v_mov_b64_e32 v[48:49], 0
	v_mov_b64_e32 v[50:51], 0
	v_mov_b64_e32 v[52:53], 0
	v_mov_b64_e32 v[54:55], 0
	v_mov_b64_e32 v[56:57], 0
	v_mov_b64_e32 v[58:59], 0
	v_mov_b64_e32 v[60:61], 0
	v_mov_b64_e32 v[62:63], 0
	v_mov_b64_e32 v[64:65], 0
	v_mov_b64_e32 v[66:67], 0
	v_mov_b64_e32 v[68:69], 0
	v_mov_b64_e32 v[70:71], 0
	v_mov_b64_e32 v[72:73], 0
	v_mov_b64_e32 v[74:75], 0
	v_mov_b64_e32 v[76:77], 0
	v_mov_b64_e32 v[78:79], 0
	v_mov_b64_e32 v[80:81], 0
	v_mov_b64_e32 v[82:83], 0
	v_mov_b64_e32 v[84:85], 0
	v_mov_b64_e32 v[86:87], 0
	v_mov_b64_e32 v[88:89], 0
	v_mov_b64_e32 v[90:91], 0
	v_mov_b64_e32 v[92:93], 0
	v_mov_b64_e32 v[94:95], 0
	v_mov_b64_e32 v[96:97], 0
	v_mov_b64_e32 v[98:99], 0
	v_mov_b64_e32 v[100:101], 0
	v_mov_b64_e32 v[102:103], 0
	v_mov_b64_e32 v[104:105], 0
	v_mov_b64_e32 v[106:107], 0
	v_mov_b64_e32 v[108:109], 0
	v_mov_b64_e32 v[110:111], 0
	v_mov_b64_e32 v[112:113], 0
	v_mov_b64_e32 v[114:115], 0
	v_mov_b64_e32 v[116:117], 0
	v_mov_b64_e32 v[118:119], 0
	v_mov_b64_e32 v[120:121], 0
	v_mov_b64_e32 v[122:123], 0
	v_mov_b64_e32 v[124:125], 0
	v_mov_b64_e32 v[126:127], 0
	s_addc_u32 s43, s45, 0
	s_mov_b32 s41, 0

.LBB0_1301:
	s_ashr_i32 s11, s10, 31
	s_lshl_b64 s[12:13], s[10:11], 19
	s_add_u32 s12, s20, s12
	s_addc_u32 s13, s21, s13
	s_ashr_i32 s9, s8, 31
	s_lshl_b64 s[14:15], s[8:9], 19
	s_add_u32 s14, s24, s14
	v_mov_b64_e32 v[0:1], 0
	v_mov_b64_e32 v[2:3], 0
	v_mov_b64_e32 v[4:5], 0
	v_mov_b64_e32 v[6:7], 0
	v_mov_b64_e32 v[8:9], 0
	v_mov_b64_e32 v[10:11], 0
	v_mov_b64_e32 v[12:13], 0
	v_mov_b64_e32 v[14:15], 0
	v_mov_b64_e32 v[16:17], 0
	v_mov_b64_e32 v[18:19], 0
	v_mov_b64_e32 v[20:21], 0
	v_mov_b64_e32 v[22:23], 0
	v_mov_b64_e32 v[24:25], 0
	v_mov_b64_e32 v[26:27], 0
	v_mov_b64_e32 v[28:29], 0
	v_mov_b64_e32 v[30:31], 0
	v_mov_b64_e32 v[32:33], 0
	v_mov_b64_e32 v[34:35], 0
	v_mov_b64_e32 v[36:37], 0
	v_mov_b64_e32 v[38:39], 0
	v_mov_b64_e32 v[40:41], 0
	v_mov_b64_e32 v[42:43], 0
	v_mov_b64_e32 v[44:45], 0
	v_mov_b64_e32 v[46:47], 0
	v_mov_b64_e32 v[48:49], 0
	v_mov_b64_e32 v[50:51], 0
	v_mov_b64_e32 v[52:53], 0
	v_mov_b64_e32 v[54:55], 0
	v_mov_b64_e32 v[56:57], 0
	v_mov_b64_e32 v[58:59], 0
	v_mov_b64_e32 v[60:61], 0
	v_mov_b64_e32 v[62:63], 0
	v_mov_b64_e32 v[64:65], 0
	v_mov_b64_e32 v[66:67], 0
	v_mov_b64_e32 v[68:69], 0
	v_mov_b64_e32 v[70:71], 0
	v_mov_b64_e32 v[72:73], 0
	v_mov_b64_e32 v[74:75], 0
	v_mov_b64_e32 v[76:77], 0
	v_mov_b64_e32 v[78:79], 0
	v_mov_b64_e32 v[80:81], 0
	v_mov_b64_e32 v[82:83], 0
	v_mov_b64_e32 v[84:85], 0
	v_mov_b64_e32 v[86:87], 0
	v_mov_b64_e32 v[88:89], 0
	v_mov_b64_e32 v[90:91], 0
	v_mov_b64_e32 v[92:93], 0
	v_mov_b64_e32 v[94:95], 0
	v_mov_b64_e32 v[96:97], 0
	v_mov_b64_e32 v[98:99], 0
	v_mov_b64_e32 v[100:101], 0
	v_mov_b64_e32 v[102:103], 0
	v_mov_b64_e32 v[104:105], 0
	v_mov_b64_e32 v[106:107], 0
	v_mov_b64_e32 v[108:109], 0
	v_mov_b64_e32 v[110:111], 0
	v_mov_b64_e32 v[112:113], 0
	v_mov_b64_e32 v[114:115], 0
	v_mov_b64_e32 v[116:117], 0
	v_mov_b64_e32 v[118:119], 0
	v_mov_b64_e32 v[120:121], 0
	v_mov_b64_e32 v[122:123], 0
	v_mov_b64_e32 v[124:125], 0
	v_mov_b64_e32 v[126:127], 0
	s_addc_u32 s15, s25, s15
	s_andn2_b64 vcc, exec, s[6:7]
	s_cbranch_vccnz .LBB0_1304
	s_and_b64 s[40:41], s[2:3], exec
	s_cselect_b32 s9, s13, s39
	s_cselect_b32 s11, s12, s38
	s_cselect_b32 s44, s15, s37
	s_cselect_b32 s45, s14, s36
	s_add_u32 s46, s36, 0x100
	s_addc_u32 s47, s37, 0
	s_add_u32 s36, s38, 0x40080
	v_mov_b64_e32 v[0:1], 0
	v_mov_b64_e32 v[2:3], 0
	v_mov_b64_e32 v[4:5], 0
	v_mov_b64_e32 v[6:7], 0
	v_mov_b64_e32 v[8:9], 0
	v_mov_b64_e32 v[10:11], 0
	v_mov_b64_e32 v[12:13], 0
	v_mov_b64_e32 v[14:15], 0
	v_mov_b64_e32 v[16:17], 0
	v_mov_b64_e32 v[18:19], 0
	v_mov_b64_e32 v[20:21], 0
	v_mov_b64_e32 v[22:23], 0
	v_mov_b64_e32 v[24:25], 0
	v_mov_b64_e32 v[26:27], 0
	v_mov_b64_e32 v[28:29], 0
	v_mov_b64_e32 v[30:31], 0
	v_mov_b64_e32 v[32:33], 0
	v_mov_b64_e32 v[34:35], 0
	v_mov_b64_e32 v[36:37], 0
	v_mov_b64_e32 v[38:39], 0
	v_mov_b64_e32 v[40:41], 0
	v_mov_b64_e32 v[42:43], 0
	v_mov_b64_e32 v[44:45], 0
	v_mov_b64_e32 v[46:47], 0
	v_mov_b64_e32 v[48:49], 0
	v_mov_b64_e32 v[50:51], 0
	v_mov_b64_e32 v[52:53], 0
	v_mov_b64_e32 v[54:55], 0
	v_mov_b64_e32 v[56:57], 0
	v_mov_b64_e32 v[58:59], 0
	v_mov_b64_e32 v[60:61], 0
	v_mov_b64_e32 v[62:63], 0
	v_mov_b64_e32 v[64:65], 0
	v_mov_b64_e32 v[66:67], 0
	v_mov_b64_e32 v[68:69], 0
	v_mov_b64_e32 v[70:71], 0
	v_mov_b64_e32 v[72:73], 0
	v_mov_b64_e32 v[74:75], 0
	v_mov_b64_e32 v[76:77], 0
	v_mov_b64_e32 v[78:79], 0
	v_mov_b64_e32 v[80:81], 0
	v_mov_b64_e32 v[82:83], 0
	v_mov_b64_e32 v[84:85], 0
	v_mov_b64_e32 v[86:87], 0
	v_mov_b64_e32 v[88:89], 0
	v_mov_b64_e32 v[90:91], 0
	v_mov_b64_e32 v[92:93], 0
	v_mov_b64_e32 v[94:95], 0
	v_mov_b64_e32 v[96:97], 0
	v_mov_b64_e32 v[98:99], 0
	v_mov_b64_e32 v[100:101], 0
	v_mov_b64_e32 v[102:103], 0
	v_mov_b64_e32 v[104:105], 0
	v_mov_b64_e32 v[106:107], 0
	v_mov_b64_e32 v[108:109], 0
	v_mov_b64_e32 v[110:111], 0
	v_mov_b64_e32 v[112:113], 0
	v_mov_b64_e32 v[114:115], 0
	v_mov_b64_e32 v[116:117], 0
	v_mov_b64_e32 v[118:119], 0
	v_mov_b64_e32 v[120:121], 0
	v_mov_b64_e32 v[122:123], 0
	v_mov_b64_e32 v[124:125], 0
	v_mov_b64_e32 v[126:127], 0
	s_addc_u32 s37, s39, 0
	s_mov_b32 s38, 0

.LBB0_1374:
	s_ashr_i32 s11, s10, 31
	s_lshl_b64 s[12:13], s[10:11], 21
	s_add_u32 s12, s20, s12
	s_addc_u32 s13, s21, s13
	s_ashr_i32 s9, s8, 31
	s_lshl_b64 s[14:15], s[8:9], 21
	s_add_u32 s14, s26, s14
	v_mov_b64_e32 v[0:1], 0
	v_mov_b64_e32 v[2:3], 0
	v_mov_b64_e32 v[4:5], 0
	v_mov_b64_e32 v[6:7], 0
	v_mov_b64_e32 v[8:9], 0
	v_mov_b64_e32 v[10:11], 0
	v_mov_b64_e32 v[12:13], 0
	v_mov_b64_e32 v[14:15], 0
	v_mov_b64_e32 v[16:17], 0
	v_mov_b64_e32 v[18:19], 0
	v_mov_b64_e32 v[20:21], 0
	v_mov_b64_e32 v[22:23], 0
	v_mov_b64_e32 v[24:25], 0
	v_mov_b64_e32 v[26:27], 0
	v_mov_b64_e32 v[28:29], 0
	v_mov_b64_e32 v[30:31], 0
	v_mov_b64_e32 v[32:33], 0
	v_mov_b64_e32 v[34:35], 0
	v_mov_b64_e32 v[36:37], 0
	v_mov_b64_e32 v[38:39], 0
	v_mov_b64_e32 v[40:41], 0
	v_mov_b64_e32 v[42:43], 0
	v_mov_b64_e32 v[44:45], 0
	v_mov_b64_e32 v[46:47], 0
	v_mov_b64_e32 v[48:49], 0
	v_mov_b64_e32 v[50:51], 0
	v_mov_b64_e32 v[52:53], 0
	v_mov_b64_e32 v[54:55], 0
	v_mov_b64_e32 v[56:57], 0
	v_mov_b64_e32 v[58:59], 0
	v_mov_b64_e32 v[60:61], 0
	v_mov_b64_e32 v[62:63], 0
	v_mov_b64_e32 v[64:65], 0
	v_mov_b64_e32 v[66:67], 0
	v_mov_b64_e32 v[68:69], 0
	v_mov_b64_e32 v[70:71], 0
	v_mov_b64_e32 v[72:73], 0
	v_mov_b64_e32 v[74:75], 0
	v_mov_b64_e32 v[76:77], 0
	v_mov_b64_e32 v[78:79], 0
	v_mov_b64_e32 v[80:81], 0
	v_mov_b64_e32 v[82:83], 0
	v_mov_b64_e32 v[84:85], 0
	v_mov_b64_e32 v[86:87], 0
	v_mov_b64_e32 v[88:89], 0
	v_mov_b64_e32 v[90:91], 0
	v_mov_b64_e32 v[92:93], 0
	v_mov_b64_e32 v[94:95], 0
	v_mov_b64_e32 v[96:97], 0
	v_mov_b64_e32 v[98:99], 0
	v_mov_b64_e32 v[100:101], 0
	v_mov_b64_e32 v[102:103], 0
	v_mov_b64_e32 v[104:105], 0
	v_mov_b64_e32 v[106:107], 0
	v_mov_b64_e32 v[108:109], 0
	v_mov_b64_e32 v[110:111], 0
	v_mov_b64_e32 v[112:113], 0
	v_mov_b64_e32 v[114:115], 0
	v_mov_b64_e32 v[116:117], 0
	v_mov_b64_e32 v[118:119], 0
	v_mov_b64_e32 v[120:121], 0
	v_mov_b64_e32 v[122:123], 0
	v_mov_b64_e32 v[124:125], 0
	v_mov_b64_e32 v[126:127], 0
	s_addc_u32 s15, s27, s15
	s_andn2_b64 vcc, exec, s[6:7]
	s_cbranch_vccnz .LBB0_1377
	s_and_b64 s[24:25], s[2:3], exec
	s_cselect_b32 s9, s13, s37
	s_cselect_b32 s11, s12, s36
	s_cselect_b32 s17, s15, s19
	s_cselect_b32 s24, s14, s18
	s_add_u32 s25, s18, 0x100
	s_addc_u32 s48, s19, 0
	s_add_u32 s18, s36, 0x100080
	v_mov_b64_e32 v[0:1], 0
	v_mov_b64_e32 v[2:3], 0
	v_mov_b64_e32 v[4:5], 0
	v_mov_b64_e32 v[6:7], 0
	v_mov_b64_e32 v[8:9], 0
	v_mov_b64_e32 v[10:11], 0
	v_mov_b64_e32 v[12:13], 0
	v_mov_b64_e32 v[14:15], 0
	v_mov_b64_e32 v[16:17], 0
	v_mov_b64_e32 v[18:19], 0
	v_mov_b64_e32 v[20:21], 0
	v_mov_b64_e32 v[22:23], 0
	v_mov_b64_e32 v[24:25], 0
	v_mov_b64_e32 v[26:27], 0
	v_mov_b64_e32 v[28:29], 0
	v_mov_b64_e32 v[30:31], 0
	v_mov_b64_e32 v[32:33], 0
	v_mov_b64_e32 v[34:35], 0
	v_mov_b64_e32 v[36:37], 0
	v_mov_b64_e32 v[38:39], 0
	v_mov_b64_e32 v[40:41], 0
	v_mov_b64_e32 v[42:43], 0
	v_mov_b64_e32 v[44:45], 0
	v_mov_b64_e32 v[46:47], 0
	v_mov_b64_e32 v[48:49], 0
	v_mov_b64_e32 v[50:51], 0
	v_mov_b64_e32 v[52:53], 0
	v_mov_b64_e32 v[54:55], 0
	v_mov_b64_e32 v[56:57], 0
	v_mov_b64_e32 v[58:59], 0
	v_mov_b64_e32 v[60:61], 0
	v_mov_b64_e32 v[62:63], 0
	v_mov_b64_e32 v[64:65], 0
	v_mov_b64_e32 v[66:67], 0
	v_mov_b64_e32 v[68:69], 0
	v_mov_b64_e32 v[70:71], 0
	v_mov_b64_e32 v[72:73], 0
	v_mov_b64_e32 v[74:75], 0
	v_mov_b64_e32 v[76:77], 0
	v_mov_b64_e32 v[78:79], 0
	v_mov_b64_e32 v[80:81], 0
	v_mov_b64_e32 v[82:83], 0
	v_mov_b64_e32 v[84:85], 0
	v_mov_b64_e32 v[86:87], 0
	v_mov_b64_e32 v[88:89], 0
	v_mov_b64_e32 v[90:91], 0
	v_mov_b64_e32 v[92:93], 0
	v_mov_b64_e32 v[94:95], 0
	v_mov_b64_e32 v[96:97], 0
	v_mov_b64_e32 v[98:99], 0
	v_mov_b64_e32 v[100:101], 0
	v_mov_b64_e32 v[102:103], 0
	v_mov_b64_e32 v[104:105], 0
	v_mov_b64_e32 v[106:107], 0
	v_mov_b64_e32 v[108:109], 0
	v_mov_b64_e32 v[110:111], 0
	v_mov_b64_e32 v[112:113], 0
	v_mov_b64_e32 v[114:115], 0
	v_mov_b64_e32 v[116:117], 0
	v_mov_b64_e32 v[118:119], 0
	v_mov_b64_e32 v[120:121], 0
	v_mov_b64_e32 v[122:123], 0
	v_mov_b64_e32 v[124:125], 0
	v_mov_b64_e32 v[126:127], 0
	s_addc_u32 s19, s37, 0
	s_mov_b32 s36, 0

.LBB0_1403:
	v_mov_b64_e32 v[0:1], 0
	v_mov_b64_e32 v[2:3], 0
	v_mov_b64_e32 v[4:5], 0
	v_mov_b64_e32 v[6:7], 0
	v_mov_b64_e32 v[8:9], 0
	v_mov_b64_e32 v[10:11], 0
	v_mov_b64_e32 v[12:13], 0
	v_mov_b64_e32 v[14:15], 0
	v_mov_b64_e32 v[16:17], 0
	v_mov_b64_e32 v[18:19], 0
	v_mov_b64_e32 v[20:21], 0
	v_mov_b64_e32 v[22:23], 0
	v_mov_b64_e32 v[24:25], 0
	v_mov_b64_e32 v[26:27], 0
	v_mov_b64_e32 v[28:29], 0
	v_mov_b64_e32 v[30:31], 0
	v_mov_b64_e32 v[32:33], 0
	v_mov_b64_e32 v[34:35], 0
	v_mov_b64_e32 v[36:37], 0
	v_mov_b64_e32 v[38:39], 0
	v_mov_b64_e32 v[40:41], 0
	v_mov_b64_e32 v[42:43], 0
	v_mov_b64_e32 v[44:45], 0
	v_mov_b64_e32 v[46:47], 0
	v_mov_b64_e32 v[48:49], 0
	v_mov_b64_e32 v[50:51], 0
	v_mov_b64_e32 v[52:53], 0
	v_mov_b64_e32 v[54:55], 0
	v_mov_b64_e32 v[56:57], 0
	v_mov_b64_e32 v[58:59], 0
	v_mov_b64_e32 v[60:61], 0
	v_mov_b64_e32 v[62:63], 0
	v_mov_b64_e32 v[64:65], 0
	v_mov_b64_e32 v[66:67], 0
	v_mov_b64_e32 v[68:69], 0
	v_mov_b64_e32 v[70:71], 0
	v_mov_b64_e32 v[72:73], 0
	v_mov_b64_e32 v[74:75], 0
	v_mov_b64_e32 v[76:77], 0
	v_mov_b64_e32 v[78:79], 0
	v_mov_b64_e32 v[80:81], 0
	v_mov_b64_e32 v[82:83], 0
	v_mov_b64_e32 v[84:85], 0
	v_mov_b64_e32 v[86:87], 0
	v_mov_b64_e32 v[88:89], 0
	v_mov_b64_e32 v[90:91], 0
	v_mov_b64_e32 v[92:93], 0
	v_mov_b64_e32 v[94:95], 0
	v_mov_b64_e32 v[96:97], 0
	v_mov_b64_e32 v[98:99], 0
	v_mov_b64_e32 v[100:101], 0
	v_mov_b64_e32 v[102:103], 0
	v_mov_b64_e32 v[104:105], 0
	v_mov_b64_e32 v[106:107], 0
	v_mov_b64_e32 v[108:109], 0
	v_mov_b64_e32 v[110:111], 0
	v_mov_b64_e32 v[112:113], 0
	v_mov_b64_e32 v[114:115], 0
	v_mov_b64_e32 v[116:117], 0
	v_mov_b64_e32 v[118:119], 0
	v_mov_b64_e32 v[120:121], 0
	v_mov_b64_e32 v[122:123], 0
	v_mov_b64_e32 v[124:125], 0
	v_mov_b64_e32 v[126:127], 0
	s_andn2_b64 vcc, exec, s[10:11]
	s_cbranch_vccnz .LBB0_1407
	s_add_u32 s15, s18, 0x100
	s_addc_u32 s48, s19, 0
	s_add_u32 s18, s36, 0x100080
	v_mov_b64_e32 v[0:1], 0
	v_mov_b64_e32 v[2:3], 0
	v_mov_b64_e32 v[4:5], 0
	v_mov_b64_e32 v[6:7], 0
	v_mov_b64_e32 v[8:9], 0
	v_mov_b64_e32 v[10:11], 0
	v_mov_b64_e32 v[12:13], 0
	v_mov_b64_e32 v[14:15], 0
	v_mov_b64_e32 v[16:17], 0
	v_mov_b64_e32 v[18:19], 0
	v_mov_b64_e32 v[20:21], 0
	v_mov_b64_e32 v[22:23], 0
	v_mov_b64_e32 v[24:25], 0
	v_mov_b64_e32 v[26:27], 0
	v_mov_b64_e32 v[28:29], 0
	v_mov_b64_e32 v[30:31], 0
	v_mov_b64_e32 v[32:33], 0
	v_mov_b64_e32 v[34:35], 0
	v_mov_b64_e32 v[36:37], 0
	v_mov_b64_e32 v[38:39], 0
	v_mov_b64_e32 v[40:41], 0
	v_mov_b64_e32 v[42:43], 0
	v_mov_b64_e32 v[44:45], 0
	v_mov_b64_e32 v[46:47], 0
	v_mov_b64_e32 v[48:49], 0
	v_mov_b64_e32 v[50:51], 0
	v_mov_b64_e32 v[52:53], 0
	v_mov_b64_e32 v[54:55], 0
	v_mov_b64_e32 v[56:57], 0
	v_mov_b64_e32 v[58:59], 0
	v_mov_b64_e32 v[60:61], 0
	v_mov_b64_e32 v[62:63], 0
	v_mov_b64_e32 v[64:65], 0
	v_mov_b64_e32 v[66:67], 0
	v_mov_b64_e32 v[68:69], 0
	v_mov_b64_e32 v[70:71], 0
	v_mov_b64_e32 v[72:73], 0
	v_mov_b64_e32 v[74:75], 0
	v_mov_b64_e32 v[76:77], 0
	v_mov_b64_e32 v[78:79], 0
	v_mov_b64_e32 v[80:81], 0
	v_mov_b64_e32 v[82:83], 0
	v_mov_b64_e32 v[84:85], 0
	v_mov_b64_e32 v[86:87], 0
	v_mov_b64_e32 v[88:89], 0
	v_mov_b64_e32 v[90:91], 0
	v_mov_b64_e32 v[92:93], 0
	v_mov_b64_e32 v[94:95], 0
	v_mov_b64_e32 v[96:97], 0
	v_mov_b64_e32 v[98:99], 0
	v_mov_b64_e32 v[100:101], 0
	v_mov_b64_e32 v[102:103], 0
	v_mov_b64_e32 v[104:105], 0
	v_mov_b64_e32 v[106:107], 0
	v_mov_b64_e32 v[108:109], 0
	v_mov_b64_e32 v[110:111], 0
	v_mov_b64_e32 v[112:113], 0
	v_mov_b64_e32 v[114:115], 0
	v_mov_b64_e32 v[116:117], 0
	v_mov_b64_e32 v[118:119], 0
	v_mov_b64_e32 v[120:121], 0
	v_mov_b64_e32 v[122:123], 0
	v_mov_b64_e32 v[124:125], 0
	v_mov_b64_e32 v[126:127], 0
	s_addc_u32 s19, s37, 0
	s_mov_b32 s36, 0
